# P8/P9 order mixed across workgroups: WGs with id bit 3 set run the gate-up tiles (P9) first and the down-proj tile (P8) second, the rest keep P8 then P9
# speedup vs baseline: 1.0157x; 1.0060x over previous
.LBB0_1547:
	s_or_b64 exec, exec, s[2:3]
	s_waitcnt lgkmcnt(0)
	s_barrier
	s_nop 0
	s_nop 0
	s_nop 0
	s_nop 0
	s_nop 0
	s_nop 0
	s_nop 0
	s_nop 0
	s_nop 0
	s_nop 0
	s_mov_b32 s101, 0
.LBB0_1548:
	s_bitcmp1_b32 s33, 3
	s_cbranch_scc0 .Lp8_enter
	s_cmp_lg_u32 s101, 0
	s_cbranch_scc1 .Lp8_enter
	s_mov_b32 s101, 1
	s_branch .LBB0_1602
	s_nop 0
	s_nop 0
	s_nop 0
	s_nop 0
	s_nop 0
	s_nop 0
	s_nop 0
	s_nop 0
	s_nop 0
	s_nop 0

.LBB0_1602:
	s_cmp_gt_i32 s85, 9
	s_cselect_b64 s[0:1], -1, 0
	s_and_b64 s[2:3], s[8:9], s[0:1]
	s_andn2_b64 vcc, exec, s[2:3]
	s_cmp_eq_u32 s101, 2
	s_cbranch_scc0 .LBB0_1656
	s_add_u32 s48, s48, 0x4800000
	s_addc_u32 s49, s49, 0
	s_mov_b64 s[14:15], -1
	s_mov_b32 s101, 3
	s_branch .Lp9_exit
	s_nop 0
	s_nop 0
	s_nop 0
	s_nop 0
	s_nop 0
	s_nop 0
	s_nop 0
	s_nop 0
	s_nop 0
	s_waitcnt vmcnt(0)
	s_waitcnt lgkmcnt(0)
	s_barrier
	s_mov_b64 s[2:3], exec
	v_readlane_b32 s4, v246, 0
	v_readlane_b32 s5, v246, 1
	s_and_b64 s[4:5], s[2:3], s[4:5]
	s_mov_b64 exec, s[4:5]
	s_cbranch_execz .LBB0_1655
	s_add_i32 s4, 0, 0x23fc0
	v_mov_b32_e32 v0, s4
	s_waitcnt vmcnt(0) expcnt(0) lgkmcnt(0)
	ds_read_b32 v2, v0
	s_add_i32 s4, 0, 0x23fc4
	v_mov_b32_e32 v0, s4
	ds_read_b32 v0, v0
	s_waitcnt lgkmcnt(1)
	v_cmp_ne_u32_e32 vcc, 0, v2
	s_cbranch_vccnz .LBB0_1619
	s_load_dwordx2 s[8:9], s[96:97], 0x4
	s_add_u32 s4, s82, 0x80200
	s_addc_u32 s5, s83, 0
	s_add_u32 s6, s82, 0x80400
	s_addc_u32 s7, s83, 0
	s_waitcnt lgkmcnt(0)
	s_mul_i32 s50, s8, s89
	s_add_u32 s8, s82, 0x80500
	s_mul_i32 s50, s50, s9
	s_addc_u32 s9, s83, 0
	s_add_u32 s10, s82, 0x80600
	s_addc_u32 s11, s83, 0
	s_add_u32 s14, s82, 0x80700
	s_addc_u32 s15, s83, 0
	s_add_u32 s16, s82, 0x80800
	s_addc_u32 s17, s83, 0
	s_add_u32 s18, s82, 0x80900
	s_addc_u32 s19, s83, 0
	s_add_u32 s20, s82, 0x80a00
	s_addc_u32 s21, s83, 0
	s_add_u32 s22, s82, 0x80b00
	s_addc_u32 s23, s83, 0
	s_add_u32 s24, s82, 0x80c00
	s_addc_u32 s25, s83, 0
	s_add_u32 s26, s82, 0x80d00
	s_addc_u32 s27, s83, 0
	s_add_u32 s28, s82, 0x80e00
	s_addc_u32 s29, s83, 0
	s_add_u32 s30, s82, 0x80f00
	s_addc_u32 s31, s83, 0
	s_add_u32 s34, s82, 0x81000
	s_addc_u32 s35, s83, 0
	s_add_u32 s36, s82, 0x81100
	s_addc_u32 s37, s83, 0
	s_add_u32 s38, s82, 0x81200
	s_addc_u32 s39, s83, 0
	s_add_u32 s40, s82, 0x81300
	s_addc_u32 s41, s83, 0
	s_mov_b32 s51, 1
	v_mov_b32_e32 v16, 0
	s_branch .LBB0_1607

.LBB0_1673:
	s_cmp_eq_u32 s101, 1
	s_cbranch_scc0 .Lp9_exit
	s_mov_b32 s101, 2
	s_sub_u32 s48, s48, 0x4800000
	s_subb_u32 s49, s49, 0
	s_mov_b64 s[0:1], -1
	s_branch .LBB0_1548
	s_nop 0
	s_nop 0
	s_nop 0
	s_nop 0
	s_nop 0
	s_nop 0
	s_nop 0
	s_nop 0
